# grid barrier spin loops poll without s_sleep
# baseline (speedup 1.0000x reference)
.LBB0_1453:
	s_and_b32 s1, s0, 0xff
	s_mov_b64 s[18:19], -1
	s_cmp_lg_u32 s1, 0
	s_mov_b64 s[22:23], -1
	s_nop 0
	s_cbranch_scc1 .LBB0_1456
	v_readlane_b32 s2, v254, 23
	v_readlane_b32 s3, v254, 24
	s_nop 4
	global_load_dword v2, v1, s[2:3] offset:512 sc1
	s_waitcnt vmcnt(0)
	v_cmp_eq_u32_e32 vcc, 0, v2
	s_cbranch_vccnz .LBB0_1458
	s_mov_b64 s[22:23], 0
	s_mov_b64 s[20:21], -1

.LBB0_1467:
	s_and_b32 s1, s0, 0xff
	s_mov_b64 s[20:21], -1
	s_cmp_lg_u32 s1, 0
	s_mov_b64 s[24:25], -1
	s_nop 0
	s_cbranch_scc1 .LBB0_1470
	global_load_dword v2, v1, s[12:13] sc1
	s_waitcnt vmcnt(0)
	v_cmp_eq_u32_e32 vcc, 0, v2
	s_cbranch_vccnz .LBB0_1472
	s_mov_b64 s[24:25], 0
	s_mov_b64 s[22:23], -1
